# fnlocal: final RMSNorm rows assigned per XCD of the producing out-proj tiles, 16 consecutive rows per wave; on top of v90
# baseline (speedup 1.0000x reference)
; #define GAS __attribute__((address_space(1)))
; __device__ __forceinline__ int lane_id_opaque() { int l; asm volatile("v_mbcnt_lo_u32_b32 %0, -1, 0\n\tv_mbcnt_hi_u32_b32 %0, -1, %0" : "=&v"(l)); return l; }
; __global__ void __launch_bounds__(NTHREADS, 2) __attribute__((amdgpu_waves_per_eu(2, 2))) hymba_fwd(Params p) {
;     ...
;     {
;         int tidf = wave_s * 64 + lane_id_opaque(); asm volatile("" : "+v"(tidf));
;         const int tid = tidf, lane = tid & 63, wave = tid >> 6;
;         const int gw = vcu * 8 + wave, NGW = G * 8;
;         f32x4 gf[4][2];
; #pragma unroll
;         for (int j = 0; j < 4; ++j) { gf[j][0] = ((const GAS f32x4*)p.final_norm)[2 * (lane + 64 * j)]; gf[j][1] = ((const GAS f32x4*)p.final_norm)[2 * (lane + 64 * j) + 1]; }
;         for (int row = gw; row < T_TOK; row += NGW) {
;             const GAS u32x4* yr = (const GAS u32x4*)((const GAS bf16_t*)(ws + WS_XN) + (size_t)row * 2048);
;             GAS f32x4* orow = (GAS f32x4*)((GAS float*)p.out + (size_t)row * 2048);
;             const float rs = rsqrtf(((const GAS float*)SSF)[row] * (1.0f / 2048.0f) + EPS);
.LBB0_772:
	v_mbcnt_lo_u32_b32 v0, -1, 0
	v_mbcnt_hi_u32_b32 v0, -1, v0
	v_readlane_b32 s0, v254, 0
	v_add_u32_e32 v0, s81, v0
	s_lshl_b32 s2, s0, 3
	v_ashrrev_i32_e32 v32, 6, v0
	v_add_u32_e32 v38, s2, v32
	s_mov_b32 s0, 0x8000
	v_cmp_gt_i32_e32 vcc, s0, v38
	s_and_saveexec_b64 s[0:1], vcc
	s_cbranch_execz .LBB0_775
	v_readlane_b32 s4, v254, 8
	v_and_b32_e32 v39, 63, v0
	v_readlane_b32 s12, v254, 16
	v_readlane_b32 s13, v254, 17
	v_readlane_b32 s14, v254, 18
	v_readlane_b32 s15, v254, 19
	v_readlane_b32 s16, v254, 20
	v_readlane_b32 s17, v254, 21
	v_lshlrev_b32_e32 v36, 5, v39
	v_mov_b32_e32 v37, 0
	v_readlane_b32 s18, v254, 22
	v_readlane_b32 s19, v254, 23
	s_mov_b64 s[12:13], s[16:17]
	v_lshl_add_u64 v[24:25], s[12:13], 0, v[36:37]
	s_mov_b64 s[0:1], 0x1000
	v_lshl_add_u64 v[26:27], v[24:25], 0, s[0:1]
	s_movk_i32 s0, 0x1000
	global_load_dwordx4 v[0:3], v36, s[12:13] offset:16
	global_load_dwordx4 v[4:7], v36, s[12:13]
	global_load_dwordx4 v[8:11], v36, s[12:13] offset:2064
	global_load_dwordx4 v[12:15], v36, s[12:13] offset:2048
	v_add_co_u32_e32 v34, vcc, s0, v24
	s_mov_b64 s[0:1], 0x1800
	s_nop 0
	v_addc_co_u32_e32 v35, vcc, 0, v25, vcc
	global_load_dwordx4 v[16:19], v[34:35], off
	global_load_dwordx4 v[20:23], v[26:27], off offset:16
	v_lshl_add_u64 v[40:41], v[24:25], 0, s[0:1]
	global_load_dwordx4 v[24:27], v[34:35], off offset:2048
	global_load_dwordx4 v[28:31], v[40:41], off offset:16
	v_ashrrev_i32_e32 v33, 31, v32
	s_ashr_i32 s3, s2, 31
	v_lshl_add_u64 v[40:41], v[32:33], 0, s[2:3]
	v_lshl_add_u64 v[32:33], v[40:41], 2, s[38:39]
	v_lshlrev_b64 v[34:35], 12, v[40:41]
	v_lshlrev_b64 v[40:41], 13, v[40:41]
	v_readlane_b32 s5, v254, 9
	v_readlane_b32 s6, v254, 10
	v_readlane_b32 s7, v254, 11
	s_mov_b64 s[14:15], s[18:19]
	s_lshl_b32 s0, s70, 3
	v_lshl_or_b32 v34, v39, 4, v34
	v_or_b32_e32 v40, v40, v36
	v_readlane_b32 s8, v254, 12
	v_readlane_b32 s9, v254, 13
	v_readlane_b32 s10, v254, 14
	v_readlane_b32 s11, v254, 15
	s_ashr_i32 s1, s0, 31
	v_lshl_add_u64 v[34:35], s[58:59], 0, v[34:35]
	s_mov_b64 s[4:5], 0xc00
	v_lshl_add_u64 v[36:37], s[14:15], 0, v[40:41]
	s_mov_b64 s[6:7], 0x1810
	s_lshl_b64 s[2:3], s[0:1], 2
	v_lshl_add_u64 v[34:35], v[34:35], 0, s[4:5]
	s_lshl_b64 s[4:5], s[0:1], 12
	v_lshl_add_u64 v[36:37], v[36:37], 0, s[6:7]
	s_lshl_b64 s[6:7], s[0:1], 13
	s_mov_b64 s[8:9], 0
	v_mov_b32_e32 v39, 0x358637bd
	s_mov_b32 s1, 0x800000
	s_movk_i32 s10, 0xf000
	s_movk_i32 s11, 0x7fff
	v_mbcnt_lo_u32_b32 v88, -1, 0
	v_mbcnt_hi_u32_b32 v88, -1, v88
	v_mov_b32_e32 v89, 0
	v_lshlrev_b32_e32 v90, 4, v88
	v_add_u32_e32 v91, 0x1000, v90
	global_load_dwordx4 v[0:3], v90, s[16:17]
	global_load_dwordx4 v[4:7], v90, s[16:17] offset:1024
	global_load_dwordx4 v[8:11], v90, s[16:17] offset:2048
	global_load_dwordx4 v[12:15], v90, s[16:17] offset:3072
	global_load_dwordx4 v[16:19], v91, s[16:17]
	global_load_dwordx4 v[20:23], v91, s[16:17] offset:1024
	global_load_dwordx4 v[24:27], v91, s[16:17] offset:2048
	global_load_dwordx4 v[28:31], v91, s[16:17] offset:3072
	v_readlane_b32 s8, v254, 0
	s_nop 1
	s_and_b32 s9, s8, 7
	s_lshl_b32 s9, s9, 12
	s_lshr_b32 s8, s8, 3
	s_lshl_b32 s8, s8, 7
	s_add_u32 s9, s9, s8
	s_lshr_b32 s8, s81, 6
	s_lshl_b32 s8, s8, 4
	s_add_u32 s9, s9, s8
	s_lshl_b32 s8, s9, 2
	s_add_u32 s10, s38, s8
	s_addc_u32 s11, s39, 0
	v_mov_b32_e32 v32, s10
	v_mov_b32_e32 v33, s11
	s_lshl_b32 s8, s9, 12
	s_add_u32 s10, s58, s8
	s_addc_u32 s11, s59, 0
	v_lshlrev_b32_e32 v92, 3, v88
	v_mov_b32_e32 v93, 0
	v_lshl_add_u64 v[34:35], s[10:11], 0, v[92:93]
	s_lshl_b32 s8, s9, 13
	s_add_u32 s10, s18, s8
	s_addc_u32 s11, s19, 0
	v_lshlrev_b32_e32 v92, 4, v88
	v_lshl_add_u64 v[36:37], s[10:11], 0, v[92:93]
	s_mov_b64 s[2:3], 4
	s_mov_b64 s[4:5], 0x1000
	s_mov_b64 s[6:7], 0x2000
	v_add_co_u32_e32 v58, vcc, 0x1000, v36
	s_nop 1
	v_addc_co_u32_e32 v59, vcc, 0, v37, vcc
	s_mov_b32 s13, 8
	global_load_dword v56, v[32:33], off
	global_load_dwordx2 v[40:41], v[34:35], off
	global_load_dwordx2 v[42:43], v[34:35], off offset:512
	global_load_dwordx2 v[44:45], v[34:35], off offset:1024
	global_load_dwordx2 v[46:47], v[34:35], off offset:1536
	global_load_dwordx2 v[48:49], v[34:35], off offset:2048
	global_load_dwordx2 v[50:51], v[34:35], off offset:2560
	global_load_dwordx2 v[52:53], v[34:35], off offset:3072
	global_load_dwordx2 v[54:55], v[34:35], off offset:3584
	v_lshl_add_u64 v[32:33], v[32:33], 0, s[2:3]
	v_lshl_add_u64 v[34:35], v[34:35], 0, s[4:5]
